# GEMM2 gating epilogue (mLSTM columns): each half-tile load batch re-ordered so all loads and their address arithmetic issue first and the consumers follow behind counted vmcnt waits (removes two to th
# baseline (speedup 1.0000x reference)
.LBB0_608:
	s_andn2_b64 vcc, exec, s[0:1]
	s_cbranch_vccnz .LBB0_610
	s_lshl_b32 s0, s2, 7
	s_lshl_b32 s21, s26, 8
	s_addk_i32 s0, 0xf800
	s_add_i32 s21, s21, s43
	v_or_b32_e32 v174, s0, v223
	s_lshr_b32 s19, s0, 8
	s_ashr_i32 s0, s21, 10
	s_and_b32 s0, s0, 0x1ffffff8
	s_add_i32 s0, s0, s19
	v_or_b32_e32 v210, s21, v220
	s_lshl_b32 s0, s0, 3
	v_mov_b64_e32 v[152:153], s[68:69]
	s_ashr_i32 s1, s0, 31
	v_mad_i64_i32 v[136:137], s[28:29], v210, s40, v[152:153]
	v_lshlrev_b64 v[154:155], 1, v[174:175]
	v_readlane_b32 s52, v250, 19
	s_lshl_b64 s[0:1], s[0:1], 15
	v_lshl_add_u64 v[136:137], v[136:137], 0, v[154:155]
	v_readlane_b32 s62, v250, 29
	v_readlane_b32 s63, v250, 30
	s_add_u32 s0, s41, s0
	v_add_co_u32_e32 v202, vcc, s75, v136
	v_bitop3_b32 v136, s21, v228, v220 bitop3:0xc8
	v_lshl_add_u64 v[132:133], v[174:175], 2, s[62:63]
	s_addc_u32 s1, s42, s1
	v_lshlrev_b32_e32 v174, 2, v136
	v_addc_co_u32_e32 v203, vcc, 0, v137, vcc
	v_lshl_add_u64 v[136:137], s[0:1], 0, v[174:175]
	v_add_co_u32_e32 v138, vcc, s76, v136
	global_load_dwordx4 v[128:131], v[132:133], off offset:16
	s_nop 0
	global_load_dwordx4 v[132:135], v[132:133], off
	v_addc_co_u32_e32 v139, vcc, 0, v137, vcc
	v_add_co_u32_e32 v140, vcc, s47, v136
	global_load_dword v212, v174, s[0:1]
	s_nop 0
	v_addc_co_u32_e32 v141, vcc, 0, v137, vcc
	v_add_co_u32_e32 v142, vcc, s77, v136
	s_nop 1
	v_addc_co_u32_e32 v143, vcc, 0, v137, vcc
	global_load_dwordx4 v[148:151], v[202:203], off
	global_load_dword v215, v[138:139], off
	global_load_dword v216, v[140:141], off
	global_load_dword v219, v[142:143], off
	v_add_co_u32_e32 v138, vcc, s39, v136
	s_nop 1
	v_addc_co_u32_e32 v139, vcc, 0, v137, vcc
	v_add_co_u32_e32 v140, vcc, s86, v136
	s_addk_i32 s21, 0x80
	s_nop 0
	v_addc_co_u32_e32 v141, vcc, 0, v137, vcc
	v_add_co_u32_e32 v142, vcc, s46, v136
	v_readlane_b32 s53, v250, 20
	s_nop 0
	v_addc_co_u32_e32 v143, vcc, 0, v137, vcc
	v_add_co_u32_e32 v136, vcc, s87, v136
	v_readlane_b32 s54, v250, 21
	s_nop 0
	v_addc_co_u32_e32 v137, vcc, 0, v137, vcc
	global_load_dword v213, v[138:139], off
	global_load_dword v214, v[140:141], off
	global_load_dword v217, v[142:143], off
	global_load_dword v218, v[136:137], off
	v_or_b32_e32 v136, 16, v210
	v_mad_i64_i32 v[136:137], s[28:29], v136, s40, v[152:153]
	v_lshl_add_u64 v[136:137], v[136:137], 0, v[154:155]
	v_add_co_u32_e32 v190, vcc, s75, v136
	v_bitop3_b32 v136, v210, s88, 16 bitop3:0xc8
	v_lshlrev_b32_e32 v174, 2, v136
	v_addc_co_u32_e32 v191, vcc, 0, v137, vcc
	v_lshl_add_u64 v[136:137], s[0:1], 0, v[174:175]
	v_add_co_u32_e32 v138, vcc, s76, v136
	global_load_dword v156, v174, s[0:1]
	s_nop 0
	v_addc_co_u32_e32 v139, vcc, 0, v137, vcc
	v_add_co_u32_e32 v140, vcc, s47, v136
	v_readlane_b32 s55, v250, 22
	s_nop 0
	v_addc_co_u32_e32 v141, vcc, 0, v137, vcc
	v_add_co_u32_e32 v142, vcc, s77, v136
	v_readlane_b32 s56, v250, 23
	s_nop 0
	v_addc_co_u32_e32 v143, vcc, 0, v137, vcc
	global_load_dwordx4 v[144:147], v[190:191], off
	global_load_dword v205, v[138:139], off
	global_load_dword v208, v[140:141], off
	global_load_dword v207, v[142:143], off
	v_add_co_u32_e32 v138, vcc, s39, v136
	v_readlane_b32 s57, v250, 24
	s_nop 0
	v_addc_co_u32_e32 v139, vcc, 0, v137, vcc
	v_add_co_u32_e32 v140, vcc, s86, v136
	v_readlane_b32 s58, v250, 25
	s_nop 0
	v_addc_co_u32_e32 v141, vcc, 0, v137, vcc
	v_add_co_u32_e32 v142, vcc, s46, v136
	v_readlane_b32 s59, v250, 26
	s_nop 0
	v_addc_co_u32_e32 v143, vcc, 0, v137, vcc
	v_add_co_u32_e32 v136, vcc, s87, v136
	v_readlane_b32 s60, v250, 27
	s_nop 0
	v_addc_co_u32_e32 v137, vcc, 0, v137, vcc
	global_load_dword v157, v[138:139], off
	global_load_dword v204, v[140:141], off
	global_load_dword v209, v[142:143], off
	global_load_dword v206, v[136:137], off
	v_or_b32_e32 v136, 32, v210
	v_mad_i64_i32 v[136:137], s[28:29], v136, s40, v[152:153]
	v_lshl_add_u64 v[136:137], v[136:137], 0, v[154:155]
	v_add_co_u32_e32 v160, vcc, s75, v136
	v_bitop3_b32 v136, v210, s89, 32 bitop3:0xc8
	v_lshlrev_b32_e32 v174, 2, v136
	v_addc_co_u32_e32 v161, vcc, 0, v137, vcc
	v_lshl_add_u64 v[136:137], s[0:1], 0, v[174:175]
	v_add_co_u32_e32 v138, vcc, s76, v136
	global_load_dword v194, v174, s[0:1]
	s_nop 0
	v_addc_co_u32_e32 v139, vcc, 0, v137, vcc
	v_add_co_u32_e32 v158, vcc, s47, v136
	s_nop 1
	v_addc_co_u32_e32 v159, vcc, 0, v137, vcc
	v_add_co_u32_e32 v162, vcc, s77, v136
	s_nop 1
	v_addc_co_u32_e32 v163, vcc, 0, v137, vcc
	global_load_dwordx4 v[140:143], v[160:161], off
	global_load_dword v197, v[138:139], off
	global_load_dword v200, v[158:159], off
	global_load_dword v199, v[162:163], off
	v_add_co_u32_e32 v138, vcc, s39, v136
	s_nop 1
	v_addc_co_u32_e32 v139, vcc, 0, v137, vcc
	v_add_co_u32_e32 v158, vcc, s86, v136
	s_nop 1
	v_addc_co_u32_e32 v159, vcc, 0, v137, vcc
	v_add_co_u32_e32 v162, vcc, s46, v136
	s_nop 1
	v_addc_co_u32_e32 v163, vcc, 0, v137, vcc
	v_add_co_u32_e32 v136, vcc, s87, v136
	s_nop 1
	v_addc_co_u32_e32 v137, vcc, 0, v137, vcc
	global_load_dword v195, v[138:139], off
	global_load_dword v196, v[158:159], off
	global_load_dword v201, v[162:163], off
	global_load_dword v198, v[136:137], off
	v_or_b32_e32 v136, 48, v210
	v_mad_i64_i32 v[136:137], s[28:29], v136, s40, v[152:153]
	v_lshl_add_u64 v[136:137], v[136:137], 0, v[154:155]
	v_add_co_u32_e32 v158, vcc, s75, v136
	v_bitop3_b32 v136, v210, s90, 48 bitop3:0xc8
	v_lshlrev_b32_e32 v174, 2, v136
	v_addc_co_u32_e32 v159, vcc, 0, v137, vcc
	v_lshl_add_u64 v[192:193], s[0:1], 0, v[174:175]
	v_add_co_u32_e32 v162, vcc, s76, v192
	s_nop 1
	v_addc_co_u32_e32 v163, vcc, 0, v193, vcc
	v_add_co_u32_e32 v186, vcc, s47, v192
	s_nop 1
	v_addc_co_u32_e32 v187, vcc, 0, v193, vcc
	v_add_co_u32_e32 v230, vcc, s77, v192
	v_readlane_b32 s61, v250, 28
	s_nop 0
	v_addc_co_u32_e32 v231, vcc, 0, v193, vcc
	global_load_dwordx4 v[136:139], v[158:159], off
	global_load_dword v163, v[162:163], off
	global_load_dword v188, v[186:187], off
	s_nop 0
	global_load_dword v187, v[230:231], off
	v_add_co_u32_e32 v230, vcc, s39, v192
	v_readlane_b32 s64, v250, 31
	s_nop 0
	v_addc_co_u32_e32 v231, vcc, 0, v193, vcc
	v_add_co_u32_e32 v232, vcc, s86, v192
	s_nop 1
	v_addc_co_u32_e32 v233, vcc, 0, v193, vcc
	v_add_co_u32_e32 v234, vcc, s46, v192
	s_nop 1
	v_addc_co_u32_e32 v235, vcc, 0, v193, vcc
	v_add_co_u32_e32 v236, vcc, s87, v192
	s_nop 1
	v_addc_co_u32_e32 v237, vcc, 0, v193, vcc
	global_load_dword v192, v174, s[0:1]
	global_load_dword v193, v[230:231], off
	global_load_dword v162, v[232:233], off
	global_load_dword v189, v[234:235], off
	global_load_dword v186, v[236:237], off
	v_mul_f32_e32 v211, 0xbfb8aa3b, v116
	v_exp_f32_e32 v211, v211
	s_waitcnt vmcnt(34)
	v_lshlrev_b32_e32 v242, 16, v148
	v_and_b32_e32 v243, 0xffff0000, v148
	v_lshlrev_b32_e32 v148, 16, v149
	s_waitcnt vmcnt(28)
	v_pk_add_f32 v[212:213], v[212:213], v[216:217]
	v_mul_f32_e32 v217, 0xbfb8aa3b, v112
	s_waitcnt vmcnt(27)
	v_pk_add_f32 v[214:215], v[214:215], v[218:219]
	v_exp_f32_e32 v217, v217
	v_and_b32_e32 v149, 0xffff0000, v149
	s_waitcnt vmcnt(19)
	v_pk_add_f32 v[156:157], v[156:157], v[208:209]
	s_waitcnt vmcnt(18)
	v_pk_add_f32 v[204:205], v[204:205], v[206:207]
	v_mov_b32_e32 v206, v156
	v_mul_f32_e32 v174, 0xbfb8aa3b, v124
	v_exp_f32_e32 v174, v174
	v_mov_b32_e32 v207, v212
	v_mov_b32_e32 v212, v157
	v_pk_add_f32 v[156:157], v[206:207], v[212:213]
	v_add_f32_e32 v174, 1.0, v174
	v_rcp_f32_e32 v216, v174
	v_add_f32_e32 v174, 1.0, v211
	v_mul_f32_e32 v211, 0xbfb8aa3b, v120
	v_exp_f32_e32 v211, v211
	v_rcp_f32_e32 v218, v174
	v_mov_b32_e32 v206, v205
	v_mov_b32_e32 v207, v215
	v_add_f32_e32 v174, 1.0, v211
	v_mul_f32_e32 v211, 0xbfb8aa3b, v125
	v_exp_f32_e32 v211, v211
	v_rcp_f32_e32 v230, v174
	v_add_f32_e32 v174, 1.0, v217
	v_mul_f32_e32 v217, 0xbfb8aa3b, v117
	v_exp_f32_e32 v219, v217
	v_rcp_f32_e32 v232, v174
	v_add_f32_e32 v174, 1.0, v211
	v_mul_f32_e32 v211, 0xbfb8aa3b, v121
	v_exp_f32_e32 v211, v211
	v_rcp_f32_e32 v217, v174
	v_add_f32_e32 v174, 1.0, v219
	v_mul_f32_e32 v219, 0xbfb8aa3b, v113
	v_exp_f32_e32 v229, v219
	v_rcp_f32_e32 v219, v174
	v_add_f32_e32 v174, 1.0, v211
	v_mul_f32_e32 v211, 0xbfb8aa3b, v126
	v_exp_f32_e32 v211, v211
	v_rcp_f32_e32 v231, v174
	v_add_f32_e32 v174, 1.0, v229
	v_mul_f32_e32 v229, 0xbfb8aa3b, v118
	v_exp_f32_e32 v229, v229
	v_rcp_f32_e32 v233, v174
	v_add_f32_e32 v174, 1.0, v211
	v_mul_f32_e32 v211, 0xbfb8aa3b, v122
	v_exp_f32_e32 v211, v211
	v_rcp_f32_e32 v234, v174
	v_add_f32_e32 v174, 1.0, v229
	v_mul_f32_e32 v229, 0xbfb8aa3b, v114
	v_exp_f32_e32 v229, v229
	v_rcp_f32_e32 v236, v174
	v_add_f32_e32 v174, 1.0, v211
	v_mul_f32_e32 v211, 0xbfb8aa3b, v127
	v_exp_f32_e32 v211, v211
	v_rcp_f32_e32 v238, v174
	v_add_f32_e32 v174, 1.0, v229
	v_rcp_f32_e32 v240, v174
	v_add_f32_e32 v174, 1.0, v211
	v_mul_f32_e32 v229, 0xbfb8aa3b, v119
	v_rcp_f32_e32 v235, v174
	v_exp_f32_e32 v229, v229
	v_mul_f32_e32 v211, 0xbfb8aa3b, v123
	v_exp_f32_e32 v211, v211
	v_pk_add_f32 v[156:157], v[206:207], v[156:157]
	v_mov_b32_e32 v205, v214
	v_pk_add_f32 v[204:205], v[204:205], v[156:157]
	v_mov_b64_e32 v[156:157], s[12:13]
	v_pk_mul_f32 v[234:235], v[234:235], v[148:149]
	v_lshlrev_b32_e32 v148, 16, v150
	v_and_b32_e32 v149, 0xffff0000, v150
	v_pk_fma_f32 v[204:205], v[204:205], s[10:11], v[156:157] op_sel_hi:[1,0,0]
	v_add_f32_e32 v174, 1.0, v229
	v_pk_mul_f32 v[230:231], v[230:231], v[148:149]
	v_mul_f32_e32 v149, 0x4b800000, v205
	v_cmp_gt_f32_e32 vcc, s70, v205
	v_mul_f32_e32 v229, 0xbfb8aa3b, v115
	v_rcp_f32_e32 v237, v174
	v_add_f32_e32 v174, 1.0, v211
	v_cndmask_b32_e32 v149, v205, v149, vcc
	v_exp_f32_e32 v229, v229
	v_rcp_f32_e32 v239, v174
	v_rsq_f32_e32 v150, v149
	v_lshlrev_b32_e32 v148, 16, v151
	v_and_b32_e32 v149, 0xffff0000, v151
	v_add_f32_e32 v174, 1.0, v229
	v_pk_mul_f32 v[206:207], v[238:239], v[148:149]
	v_mul_f32_e32 v148, 0x45800000, v150
	v_rcp_f32_e32 v241, v174
	v_pk_mul_f32 v[216:217], v[216:217], v[242:243]
	v_cndmask_b32_e32 v174, v150, v148, vcc
	v_pk_mul_f32 v[148:149], v[216:217], v[174:175] op_sel_hi:[1,0]
	v_pk_mul_f32 v[150:151], v[234:235], v[174:175] op_sel_hi:[1,0]
	v_pk_mul_f32 v[218:219], v[116:117], v[218:219]
	v_pk_mul_f32 v[236:237], v[118:119], v[236:237]
	v_pk_mul_f32 v[148:149], v[132:133], v[148:149]
	v_pk_mul_f32 v[150:151], v[134:135], v[150:151]
	v_pk_mul_f32 v[148:149], v[218:219], v[148:149]
	v_pk_mul_f32 v[150:151], v[236:237], v[150:151]
	v_cvt_pk_bf16_f32 v148, v148, v149
	v_cvt_pk_bf16_f32 v149, v150, v151
	v_pk_mul_f32 v[150:151], v[230:231], v[174:175] op_sel_hi:[1,0]
	v_pk_mul_f32 v[232:233], v[112:113], v[232:233]
	v_pk_mul_f32 v[150:151], v[128:129], v[150:151]
	v_pk_mul_f32 v[206:207], v[206:207], v[174:175] op_sel_hi:[1,0]
	v_pk_mul_f32 v[150:151], v[232:233], v[150:151]
	v_pk_mul_f32 v[208:209], v[114:115], v[240:241]
	v_cvt_pk_bf16_f32 v150, v150, v151
	v_pk_mul_f32 v[206:207], v[130:131], v[206:207]
	v_mul_f32_e32 v151, 0x4b800000, v204
	v_cmp_gt_f32_e32 vcc, s70, v204
	v_lshlrev_b32_e32 v218, 16, v144
	v_and_b32_e32 v219, 0xffff0000, v144
	v_cndmask_b32_e32 v151, v204, v151, vcc
	v_pk_mul_f32 v[204:205], v[208:209], v[206:207]
	v_rsq_f32_e32 v174, v151
	v_cvt_pk_bf16_f32 v151, v204, v205
	global_store_dwordx4 v[202:203], v[148:151], off
	v_mul_f32_e32 v203, 0xbfb8aa3b, v97
	v_exp_f32_e32 v207, v203
	v_mul_f32_e32 v149, 0xbfb8aa3b, v108
	v_exp_f32_e32 v149, v149
	v_mul_f32_e32 v150, 0xbfb8aa3b, v100
	v_exp_f32_e32 v151, v150
	v_mul_f32_e32 v148, 0x45800000, v174
	v_add_f32_e32 v149, 1.0, v149
	v_rcp_f32_e32 v150, v149
	v_add_f32_e32 v149, 1.0, v151
	v_mul_f32_e32 v151, 0xbfb8aa3b, v104
	v_cndmask_b32_e32 v148, v174, v148, vcc
	v_exp_f32_e32 v151, v151
	v_mul_f32_e32 v174, 0xbfb8aa3b, v96
	v_exp_f32_e32 v174, v174
	v_rcp_f32_e32 v202, v149
	v_add_f32_e32 v149, 1.0, v151
	v_mul_f32_e32 v151, 0xbfb8aa3b, v109
	v_rcp_f32_e32 v204, v149
	v_add_f32_e32 v149, 1.0, v174
	v_exp_f32_e32 v151, v151
	v_mul_f32_e32 v174, 0xbfb8aa3b, v101
	v_exp_f32_e32 v174, v174
	v_rcp_f32_e32 v206, v149
	v_add_f32_e32 v149, 1.0, v151
	v_rcp_f32_e32 v151, v149
	v_add_f32_e32 v149, 1.0, v174
	v_mul_f32_e32 v174, 0xbfb8aa3b, v105
	v_exp_f32_e32 v174, v174
	v_rcp_f32_e32 v203, v149
	v_pk_mul_f32 v[150:151], v[150:151], v[218:219]
	s_waitcnt vmcnt(0)
	v_pk_add_f32 v[188:189], v[192:193], v[188:189]
	v_add_f32_e32 v149, 1.0, v174
	v_mul_f32_e32 v174, 0xbfb8aa3b, v110
	v_rcp_f32_e32 v205, v149
	v_add_f32_e32 v149, 1.0, v207
	v_exp_f32_e32 v174, v174
	v_mul_f32_e32 v207, 0xbfb8aa3b, v102
	v_exp_f32_e32 v209, v207
	v_rcp_f32_e32 v207, v149
	v_add_f32_e32 v149, 1.0, v174
	v_mul_f32_e32 v174, 0xbfb8aa3b, v106
	v_rcp_f32_e32 v208, v149
	v_add_f32_e32 v149, 1.0, v209
	v_exp_f32_e32 v174, v174
	v_mul_f32_e32 v209, 0xbfb8aa3b, v98
	v_exp_f32_e32 v209, v209
	v_rcp_f32_e32 v212, v149
	v_add_f32_e32 v149, 1.0, v174
	v_mul_f32_e32 v174, 0xbfb8aa3b, v111
	v_rcp_f32_e32 v214, v149
	v_add_f32_e32 v149, 1.0, v209
	v_exp_f32_e32 v174, v174
	v_mul_f32_e32 v209, 0xbfb8aa3b, v103
	v_exp_f32_e32 v211, v209
	v_rcp_f32_e32 v216, v149
	v_add_f32_e32 v149, 1.0, v174
	v_mul_f32_e32 v174, 0xbfb8aa3b, v107
	v_rcp_f32_e32 v209, v149
	v_add_f32_e32 v149, 1.0, v211
	v_exp_f32_e32 v174, v174
	v_mul_f32_e32 v211, 0xbfb8aa3b, v99
	v_exp_f32_e32 v211, v211
	v_rcp_f32_e32 v213, v149
	v_add_f32_e32 v149, 1.0, v174
	v_rcp_f32_e32 v215, v149
	v_add_f32_e32 v149, 1.0, v211
	v_pk_mul_f32 v[150:151], v[150:151], v[148:149] op_sel_hi:[1,0]
	v_pk_mul_f32 v[202:203], v[100:101], v[202:203]
	v_pk_mul_f32 v[150:151], v[132:133], v[150:151]
	v_rcp_f32_e32 v217, v149
	v_pk_mul_f32 v[150:151], v[202:203], v[150:151]
	v_pk_mul_f32 v[202:203], v[102:103], v[212:213]
	v_cvt_pk_bf16_f32 v144, v150, v151
	v_lshlrev_b32_e32 v150, 16, v145
	v_and_b32_e32 v151, 0xffff0000, v145
	v_pk_mul_f32 v[150:151], v[208:209], v[150:151]
	v_pk_add_f32 v[162:163], v[162:163], v[186:187]
	v_pk_mul_f32 v[150:151], v[150:151], v[148:149] op_sel_hi:[1,0]
	v_mov_b32_e32 v186, v188
	v_pk_mul_f32 v[150:151], v[134:135], v[150:151]
	v_lshlrev_b32_e32 v188, 16, v136
	v_pk_mul_f32 v[150:151], v[202:203], v[150:151]
	v_pk_mul_f32 v[202:203], v[96:97], v[206:207]
	v_cvt_pk_bf16_f32 v145, v150, v151
	v_lshlrev_b32_e32 v150, 16, v146
	v_and_b32_e32 v151, 0xffff0000, v146
	v_pk_mul_f32 v[150:151], v[204:205], v[150:151]
	v_lshlrev_b32_e32 v204, 16, v140
	v_pk_mul_f32 v[150:151], v[150:151], v[148:149] op_sel_hi:[1,0]
	v_and_b32_e32 v205, 0xffff0000, v140
	v_pk_mul_f32 v[150:151], v[128:129], v[150:151]
	v_lshlrev_b32_e32 v140, 16, v141
	v_pk_mul_f32 v[150:151], v[202:203], v[150:151]
	v_and_b32_e32 v141, 0xffff0000, v141
	v_cvt_pk_bf16_f32 v146, v150, v151
	v_lshlrev_b32_e32 v150, 16, v147
	v_and_b32_e32 v151, 0xffff0000, v147
	v_pk_mul_f32 v[150:151], v[214:215], v[150:151]
	s_ashr_i32 s0, s21, 10
	v_pk_mul_f32 v[148:149], v[150:151], v[148:149] op_sel_hi:[1,0]
	v_pk_mul_f32 v[150:151], v[98:99], v[216:217]
	v_pk_mul_f32 v[148:149], v[130:131], v[148:149]
	s_and_b32 s0, s0, 0x1ffffff8
	v_pk_mul_f32 v[148:149], v[150:151], v[148:149]
	v_mul_f32_e32 v150, 0xbfb8aa3b, v88
	v_cvt_pk_bf16_f32 v147, v148, v149
	global_store_dwordx4 v[190:191], v[144:147], off
	v_exp_f32_e32 v151, v150
	v_mul_f32_e32 v150, 0xbfb8aa3b, v80
	v_mul_f32_e32 v146, 0xbfb8aa3b, v92
	v_exp_f32_e32 v148, v146
	v_mul_f32_e32 v146, 0xbfb8aa3b, v84
	v_exp_f32_e32 v149, v146
	v_exp_f32_e32 v174, v150
	v_pk_add_f32 v[144:145], v[194:195], v[200:201]
	v_mul_f32_e32 v191, 0xbfb8aa3b, v81
	v_add_f32_e32 v149, 1.0, v149
	v_rcp_f32_e32 v150, v149
	v_add_f32_e32 v149, 1.0, v151
	v_rcp_f32_e32 v190, v149
	v_add_f32_e32 v149, 1.0, v174
	v_mul_f32_e32 v151, 0xbfb8aa3b, v93
	v_mul_f32_e32 v174, 0xbfb8aa3b, v85
	v_exp_f32_e32 v151, v151
	v_exp_f32_e32 v174, v174
	v_rcp_f32_e32 v194, v149
	v_exp_f32_e32 v195, v191
	v_add_f32_e32 v149, 1.0, v151
	v_add_f32_e32 v151, 1.0, v174
	v_mul_f32_e32 v174, 0xbfb8aa3b, v89
	v_exp_f32_e32 v174, v174
	v_pk_add_f32 v[146:147], v[196:197], v[198:199]
	v_mul_f32_e32 v198, 0xbfb8aa3b, v82
	v_exp_f32_e32 v199, v198
	v_add_f32_e32 v174, 1.0, v174
	v_rcp_f32_e32 v191, v174
	v_add_f32_e32 v174, 1.0, v195
	v_mul_f32_e32 v195, 0xbfb8aa3b, v94
	v_exp_f32_e32 v196, v195
	v_mul_f32_e32 v195, 0xbfb8aa3b, v86
	v_exp_f32_e32 v197, v195
	v_rcp_f32_e32 v195, v174
	v_add_f32_e32 v174, 1.0, v196
	v_rcp_f32_e32 v196, v174
	v_add_f32_e32 v174, 1.0, v197
	v_mul_f32_e32 v197, 0xbfb8aa3b, v90
	v_exp_f32_e32 v197, v197
	v_rcp_f32_e32 v198, v174
	v_mov_b32_e32 v187, v144
	v_mov_b32_e32 v144, v189
	v_add_f32_e32 v174, 1.0, v197
	v_mul_f32_e32 v197, 0xbfb8aa3b, v95
	v_exp_f32_e32 v197, v197
	v_rcp_f32_e32 v200, v174
	v_add_f32_e32 v174, 1.0, v199
	v_mul_f32_e32 v199, 0xbfb8aa3b, v87
	v_exp_f32_e32 v199, v199
	v_rcp_f32_e32 v202, v174
	v_add_f32_e32 v174, 1.0, v197
	v_rcp_f32_e32 v197, v174
	v_add_f32_e32 v174, 1.0, v199
	v_mul_f32_e32 v199, 0xbfb8aa3b, v91
	v_pk_add_f32 v[144:145], v[186:187], v[144:145]
	v_mov_b32_e32 v186, v163
	v_mov_b32_e32 v187, v147
	v_exp_f32_e32 v201, v199
	v_pk_add_f32 v[144:145], v[186:187], v[144:145]
	v_mov_b32_e32 v163, v146
	v_pk_add_f32 v[144:145], v[162:163], v[144:145]
	v_pk_mul_f32 v[196:197], v[196:197], v[140:141]
	v_lshlrev_b32_e32 v140, 16, v142
	v_and_b32_e32 v141, 0xffff0000, v142
	v_pk_fma_f32 v[144:145], v[144:145], s[10:11], v[156:157] op_sel_hi:[1,0,0]
	v_mul_f32_e32 v199, 0xbfb8aa3b, v83
	v_pk_mul_f32 v[190:191], v[190:191], v[140:141]
	v_mul_f32_e32 v141, 0x4b800000, v145
	v_cmp_gt_f32_e32 vcc, s70, v145
	v_exp_f32_e32 v203, v199
	v_rcp_f32_e32 v199, v174
	v_add_f32_e32 v174, 1.0, v201
	v_cndmask_b32_e32 v141, v145, v141, vcc
	v_add_f32_e32 v148, 1.0, v148
	v_rcp_f32_e32 v201, v174
	v_rsq_f32_e32 v142, v141
	v_rcp_f32_e32 v148, v148
	v_rcp_f32_e32 v149, v149
	v_rcp_f32_e32 v151, v151
	v_lshlrev_b32_e32 v140, 16, v143
	v_and_b32_e32 v141, 0xffff0000, v143
	v_add_f32_e32 v174, 1.0, v203
	v_pk_mul_f32 v[146:147], v[200:201], v[140:141]
	v_mul_f32_e32 v140, 0x45800000, v142
	v_rcp_f32_e32 v203, v174
	v_pk_mul_f32 v[148:149], v[148:149], v[204:205]
	v_cndmask_b32_e32 v174, v142, v140, vcc
	v_pk_mul_f32 v[140:141], v[148:149], v[174:175] op_sel_hi:[1,0]
	v_pk_mul_f32 v[142:143], v[196:197], v[174:175] op_sel_hi:[1,0]
	v_pk_mul_f32 v[150:151], v[84:85], v[150:151]
	v_pk_mul_f32 v[198:199], v[86:87], v[198:199]
	v_pk_mul_f32 v[140:141], v[132:133], v[140:141]
	v_pk_mul_f32 v[142:143], v[134:135], v[142:143]
	v_pk_mul_f32 v[140:141], v[150:151], v[140:141]
	v_pk_mul_f32 v[142:143], v[198:199], v[142:143]
	v_cvt_pk_bf16_f32 v140, v140, v141
	v_cvt_pk_bf16_f32 v141, v142, v143
	v_pk_mul_f32 v[142:143], v[190:191], v[174:175] op_sel_hi:[1,0]
	v_pk_mul_f32 v[194:195], v[80:81], v[194:195]
	v_pk_mul_f32 v[142:143], v[128:129], v[142:143]
	v_pk_mul_f32 v[146:147], v[146:147], v[174:175] op_sel_hi:[1,0]
	v_pk_mul_f32 v[142:143], v[194:195], v[142:143]
	v_pk_mul_f32 v[162:163], v[82:83], v[202:203]
	v_cvt_pk_bf16_f32 v142, v142, v143
	v_pk_mul_f32 v[146:147], v[130:131], v[146:147]
	v_mul_f32_e32 v143, 0x4b800000, v144
	v_cmp_gt_f32_e32 vcc, s70, v144
	v_and_b32_e32 v189, 0xffff0000, v136
	s_add_i32 s0, s0, s19
	v_cndmask_b32_e32 v143, v144, v143, vcc
	v_pk_mul_f32 v[144:145], v[162:163], v[146:147]
	v_rsq_f32_e32 v148, v143
	v_cvt_pk_bf16_f32 v143, v144, v145
	global_store_dwordx4 v[160:161], v[140:143], off
	v_mul_f32_e32 v144, 0xbfb8aa3b, v64
	v_exp_f32_e32 v145, v144
	v_mul_f32_e32 v141, 0xbfb8aa3b, v76
	v_exp_f32_e32 v141, v141
	v_mul_f32_e32 v142, 0xbfb8aa3b, v68
	v_exp_f32_e32 v143, v142
	v_mul_f32_e32 v140, 0x45800000, v148
	v_add_f32_e32 v141, 1.0, v141
	v_rcp_f32_e32 v142, v141
	v_add_f32_e32 v141, 1.0, v143
	v_mul_f32_e32 v143, 0xbfb8aa3b, v72
	v_exp_f32_e32 v143, v143
	v_rcp_f32_e32 v144, v141
	v_cndmask_b32_e32 v140, v148, v140, vcc
	v_mul_f32_e32 v160, 0xbfb8aa3b, v66
	v_add_f32_e32 v141, 1.0, v143
	v_mul_f32_e32 v143, 0xbfb8aa3b, v77
	v_rcp_f32_e32 v146, v141
	v_add_f32_e32 v141, 1.0, v145
	v_exp_f32_e32 v143, v143
	v_mul_f32_e32 v145, 0xbfb8aa3b, v69
	v_exp_f32_e32 v145, v145
	v_rcp_f32_e32 v148, v141
	v_add_f32_e32 v141, 1.0, v143
	v_rcp_f32_e32 v143, v141
	v_add_f32_e32 v141, 1.0, v145
	v_mul_f32_e32 v145, 0xbfb8aa3b, v73
	v_exp_f32_e32 v147, v145
	v_mul_f32_e32 v145, 0xbfb8aa3b, v65
	v_exp_f32_e32 v149, v145
	v_rcp_f32_e32 v145, v141
	v_add_f32_e32 v141, 1.0, v147
	v_rcp_f32_e32 v147, v141
	v_add_f32_e32 v141, 1.0, v149
	v_mul_f32_e32 v149, 0xbfb8aa3b, v78
	v_exp_f32_e32 v150, v149
	v_mul_f32_e32 v149, 0xbfb8aa3b, v70
	v_exp_f32_e32 v151, v149
	v_rcp_f32_e32 v149, v141
	v_add_f32_e32 v141, 1.0, v150
	v_rcp_f32_e32 v150, v141
	v_add_f32_e32 v141, 1.0, v151
	v_mul_f32_e32 v151, 0xbfb8aa3b, v74
	v_exp_f32_e32 v151, v151
	v_exp_f32_e32 v161, v160
	v_rcp_f32_e32 v160, v141
	v_pk_mul_f32 v[142:143], v[142:143], v[188:189]
	v_add_f32_e32 v141, 1.0, v151
	v_mul_f32_e32 v151, 0xbfb8aa3b, v79
	v_rcp_f32_e32 v162, v141
	v_add_f32_e32 v141, 1.0, v161
	v_exp_f32_e32 v151, v151
	v_mul_f32_e32 v161, 0xbfb8aa3b, v71
	v_exp_f32_e32 v161, v161
	v_rcp_f32_e32 v186, v141
	v_add_f32_e32 v141, 1.0, v151
	v_rcp_f32_e32 v151, v141
	v_add_f32_e32 v141, 1.0, v161
	v_mul_f32_e32 v161, 0xbfb8aa3b, v75
	v_exp_f32_e32 v163, v161
	v_mul_f32_e32 v161, 0xbfb8aa3b, v67
	v_exp_f32_e32 v174, v161
	v_rcp_f32_e32 v161, v141
	v_add_f32_e32 v141, 1.0, v163
	v_rcp_f32_e32 v163, v141
	v_add_f32_e32 v141, 1.0, v174
	v_pk_mul_f32 v[142:143], v[142:143], v[140:141] op_sel_hi:[1,0]
	v_pk_mul_f32 v[144:145], v[68:69], v[144:145]
	v_pk_mul_f32 v[142:143], v[132:133], v[142:143]
	v_rcp_f32_e32 v187, v141
	v_pk_mul_f32 v[142:143], v[144:145], v[142:143]
	v_pk_mul_f32 v[144:145], v[70:71], v[160:161]
	v_cvt_pk_bf16_f32 v136, v142, v143
	v_lshlrev_b32_e32 v142, 16, v137
	v_and_b32_e32 v143, 0xffff0000, v137
	v_pk_mul_f32 v[142:143], v[150:151], v[142:143]
	s_lshl_b32 s0, s0, 3
	v_pk_mul_f32 v[142:143], v[142:143], v[140:141] op_sel_hi:[1,0]
	s_ashr_i32 s1, s0, 31
	v_pk_mul_f32 v[142:143], v[134:135], v[142:143]
	s_lshl_b64 s[0:1], s[0:1], 15
	v_pk_mul_f32 v[142:143], v[144:145], v[142:143]
	v_pk_mul_f32 v[144:145], v[64:65], v[148:149]
	v_cvt_pk_bf16_f32 v137, v142, v143
	v_lshlrev_b32_e32 v142, 16, v138
	v_and_b32_e32 v143, 0xffff0000, v138
	v_pk_mul_f32 v[142:143], v[146:147], v[142:143]
	s_add_u32 s0, s41, s0
	v_pk_mul_f32 v[142:143], v[142:143], v[140:141] op_sel_hi:[1,0]
	s_addc_u32 s1, s42, s1
	v_pk_mul_f32 v[142:143], v[128:129], v[142:143]
	v_mul_f32_e32 v211, 0xbfb8aa3b, v60
	v_pk_mul_f32 v[142:143], v[144:145], v[142:143]
	v_exp_f32_e32 v211, v211
	v_cvt_pk_bf16_f32 v138, v142, v143
	v_lshlrev_b32_e32 v142, 16, v139
	v_and_b32_e32 v143, 0xffff0000, v139
	v_pk_mul_f32 v[142:143], v[162:163], v[142:143]
	v_add_f32_e32 v211, 1.0, v211
	v_pk_mul_f32 v[140:141], v[142:143], v[140:141] op_sel_hi:[1,0]
	v_pk_mul_f32 v[142:143], v[66:67], v[186:187]
	v_pk_mul_f32 v[140:141], v[130:131], v[140:141]
	v_or_b32_e32 v186, s21, v220
	v_pk_mul_f32 v[140:141], v[142:143], v[140:141]
	v_readlane_b32 s65, v250, 32
	v_cvt_pk_bf16_f32 v139, v140, v141
	global_store_dwordx4 v[158:159], v[136:139], off
	v_readlane_b32 s66, v250, 33
	v_readlane_b32 s67, v250, 34
	v_mad_i64_i32 v[136:137], s[28:29], v186, s40, v[152:153]
	v_lshl_add_u64 v[136:137], v[136:137], 0, v[154:155]
	v_bitop3_b32 v138, s21, v228, v220 bitop3:0xc8
	v_add_co_u32_e32 v136, vcc, s75, v136
	v_lshlrev_b32_e32 v174, 2, v138
	s_nop 0
	v_addc_co_u32_e32 v137, vcc, 0, v137, vcc
	v_lshl_add_u64 v[138:139], s[0:1], 0, v[174:175]
	v_add_co_u32_e32 v140, vcc, s76, v138
	global_load_dword v208, v174, s[0:1]
	s_nop 0
	v_addc_co_u32_e32 v141, vcc, 0, v139, vcc
	v_add_co_u32_e32 v142, vcc, s47, v138
	s_nop 1
	v_addc_co_u32_e32 v143, vcc, 0, v139, vcc
	v_add_co_u32_e32 v144, vcc, s77, v138
	s_nop 1
	v_addc_co_u32_e32 v145, vcc, 0, v139, vcc
	global_load_dwordx4 v[148:151], v[136:137], off
	global_load_dword v213, v[140:141], off
	global_load_dword v214, v[142:143], off
	global_load_dword v217, v[144:145], off
	v_add_co_u32_e32 v136, vcc, s39, v138
	s_nop 1
	v_addc_co_u32_e32 v137, vcc, 0, v139, vcc
	v_add_co_u32_e32 v140, vcc, s86, v138
	s_nop 1
	v_addc_co_u32_e32 v141, vcc, 0, v139, vcc
	v_add_co_u32_e32 v142, vcc, s46, v138
	s_nop 1
	v_addc_co_u32_e32 v143, vcc, 0, v139, vcc
	v_add_co_u32_e32 v138, vcc, s87, v138
	s_nop 1
	v_addc_co_u32_e32 v139, vcc, 0, v139, vcc
	global_load_dword v209, v[136:137], off
	global_load_dword v212, v[140:141], off
	global_load_dword v215, v[142:143], off
	global_load_dword v216, v[138:139], off
	v_or_b32_e32 v136, 16, v186
	v_mad_i64_i32 v[136:137], s[28:29], v136, s40, v[152:153]
	v_lshl_add_u64 v[136:137], v[136:137], 0, v[154:155]
	v_bitop3_b32 v138, v186, s88, 16 bitop3:0xc8
	v_add_co_u32_e32 v136, vcc, s75, v136
	v_lshlrev_b32_e32 v174, 2, v138
	s_nop 0
	v_addc_co_u32_e32 v137, vcc, 0, v137, vcc
	v_lshl_add_u64 v[138:139], s[0:1], 0, v[174:175]
	v_add_co_u32_e32 v140, vcc, s76, v138
	global_load_dword v200, v174, s[0:1]
	s_nop 0
	v_addc_co_u32_e32 v141, vcc, 0, v139, vcc
	v_add_co_u32_e32 v142, vcc, s47, v138
	s_nop 1
	v_addc_co_u32_e32 v143, vcc, 0, v139, vcc
	v_add_co_u32_e32 v158, vcc, s77, v138
	s_nop 1
	v_addc_co_u32_e32 v159, vcc, 0, v139, vcc
	global_load_dwordx4 v[144:147], v[136:137], off
	global_load_dword v203, v[140:141], off
	global_load_dword v206, v[142:143], off
	global_load_dword v205, v[158:159], off
	v_add_co_u32_e32 v136, vcc, s39, v138
	s_nop 1
	v_addc_co_u32_e32 v137, vcc, 0, v139, vcc
	v_add_co_u32_e32 v140, vcc, s86, v138
	s_nop 1
	v_addc_co_u32_e32 v141, vcc, 0, v139, vcc
	v_add_co_u32_e32 v142, vcc, s46, v138
	s_nop 1
	v_addc_co_u32_e32 v143, vcc, 0, v139, vcc
	v_add_co_u32_e32 v138, vcc, s87, v138
	s_nop 1
	v_addc_co_u32_e32 v139, vcc, 0, v139, vcc
	global_load_dword v201, v[136:137], off
	global_load_dword v202, v[140:141], off
	global_load_dword v207, v[142:143], off
	global_load_dword v204, v[138:139], off
	v_or_b32_e32 v136, 32, v186
	v_mad_i64_i32 v[136:137], s[28:29], v136, s40, v[152:153]
	v_lshl_add_u64 v[136:137], v[136:137], 0, v[154:155]
	v_add_co_u32_e32 v160, vcc, s75, v136
	v_bitop3_b32 v136, v186, s89, 32 bitop3:0xc8
	v_lshlrev_b32_e32 v174, 2, v136
	v_addc_co_u32_e32 v161, vcc, 0, v137, vcc
	v_lshl_add_u64 v[136:137], s[0:1], 0, v[174:175]
	v_add_co_u32_e32 v138, vcc, s76, v136
	global_load_dword v192, v174, s[0:1]
	s_nop 0
	v_addc_co_u32_e32 v139, vcc, 0, v137, vcc
	v_add_co_u32_e32 v158, vcc, s47, v136
	s_nop 1
	v_addc_co_u32_e32 v159, vcc, 0, v137, vcc
	v_add_co_u32_e32 v162, vcc, s77, v136
	s_nop 1
	v_addc_co_u32_e32 v163, vcc, 0, v137, vcc
	global_load_dwordx4 v[140:143], v[160:161], off
	global_load_dword v195, v[138:139], off
	global_load_dword v198, v[158:159], off
	global_load_dword v197, v[162:163], off
	v_add_co_u32_e32 v138, vcc, s39, v136
	s_nop 1
	v_addc_co_u32_e32 v139, vcc, 0, v137, vcc
	v_add_co_u32_e32 v158, vcc, s86, v136
	s_nop 1
	v_addc_co_u32_e32 v159, vcc, 0, v137, vcc
	v_add_co_u32_e32 v162, vcc, s46, v136
	s_nop 1
	v_addc_co_u32_e32 v163, vcc, 0, v137, vcc
	v_add_co_u32_e32 v136, vcc, s87, v136
	s_nop 1
	v_addc_co_u32_e32 v137, vcc, 0, v137, vcc
	global_load_dword v193, v[138:139], off
	global_load_dword v194, v[158:159], off
	global_load_dword v199, v[162:163], off
	global_load_dword v196, v[136:137], off
	v_or_b32_e32 v136, 48, v186
	v_mad_i64_i32 v[136:137], s[28:29], v136, s40, v[152:153]
	v_lshl_add_u64 v[136:137], v[136:137], 0, v[154:155]
	v_add_co_u32_e32 v158, vcc, s75, v136
	v_bitop3_b32 v136, v186, s90, 48 bitop3:0xc8
	v_lshlrev_b32_e32 v174, 2, v136
	v_addc_co_u32_e32 v159, vcc, 0, v137, vcc
	v_lshl_add_u64 v[190:191], s[0:1], 0, v[174:175]
	v_add_co_u32_e32 v162, vcc, s76, v190
	s_nop 1
	v_addc_co_u32_e32 v163, vcc, 0, v191, vcc
	v_add_co_u32_e32 v186, vcc, s47, v190
	s_nop 1
	v_addc_co_u32_e32 v187, vcc, 0, v191, vcc
	v_add_co_u32_e32 v218, vcc, s77, v190
	s_nop 1
	v_addc_co_u32_e32 v219, vcc, 0, v191, vcc
	global_load_dwordx4 v[136:139], v[158:159], off
	global_load_dword v163, v[162:163], off
	global_load_dword v188, v[186:187], off
	s_nop 0
	global_load_dword v187, v[218:219], off
	v_add_co_u32_e32 v218, vcc, s39, v190
	s_nop 1
	v_addc_co_u32_e32 v219, vcc, 0, v191, vcc
	v_add_co_u32_e32 v230, vcc, s86, v190
	s_nop 1
	v_addc_co_u32_e32 v231, vcc, 0, v191, vcc
	v_add_co_u32_e32 v232, vcc, s46, v190
	s_nop 1
	v_addc_co_u32_e32 v233, vcc, 0, v191, vcc
	v_add_co_u32_e32 v234, vcc, s87, v190
	s_nop 1
	v_addc_co_u32_e32 v235, vcc, 0, v191, vcc
	global_load_dword v190, v174, s[0:1]
	global_load_dword v191, v[218:219], off
	global_load_dword v162, v[230:231], off
	global_load_dword v189, v[232:233], off
	global_load_dword v186, v[234:235], off
	s_waitcnt vmcnt(34)
	v_lshlrev_b32_e32 v240, 16, v148
	v_and_b32_e32 v241, 0xffff0000, v148
	v_lshlrev_b32_e32 v148, 16, v149
	v_and_b32_e32 v149, 0xffff0000, v149
	s_waitcnt vmcnt(28)
	v_pk_add_f32 v[208:209], v[208:209], v[214:215]
	v_mul_f32_e32 v214, 0xbfb8aa3b, v52
	v_exp_f32_e32 v215, v214
	v_rcp_f32_e32 v214, v211
	v_add_f32_e32 v211, 1.0, v215
	v_mul_f32_e32 v215, 0xbfb8aa3b, v56
	s_waitcnt vmcnt(27)
	v_pk_add_f32 v[212:213], v[212:213], v[216:217]
	v_exp_f32_e32 v215, v215
	v_mul_f32_e32 v216, 0xbfb8aa3b, v48
	v_exp_f32_e32 v217, v216
	v_rcp_f32_e32 v216, v211
	v_add_f32_e32 v211, 1.0, v215
	v_mul_f32_e32 v215, 0xbfb8aa3b, v61
	v_exp_f32_e32 v215, v215
	v_rcp_f32_e32 v218, v211
	v_add_f32_e32 v211, 1.0, v217
	v_mul_f32_e32 v217, 0xbfb8aa3b, v53
	v_exp_f32_e32 v217, v217
	v_rcp_f32_e32 v230, v211
	v_add_f32_e32 v211, 1.0, v215
	v_rcp_f32_e32 v215, v211
	v_add_f32_e32 v211, 1.0, v217
	v_mul_f32_e32 v217, 0xbfb8aa3b, v57
	v_exp_f32_e32 v219, v217
	v_mul_f32_e32 v217, 0xbfb8aa3b, v49
	v_exp_f32_e32 v229, v217
	v_rcp_f32_e32 v217, v211
	v_add_f32_e32 v211, 1.0, v219
	v_rcp_f32_e32 v219, v211
	v_add_f32_e32 v211, 1.0, v229
	v_mul_f32_e32 v229, 0xbfb8aa3b, v62
	v_exp_f32_e32 v229, v229
	v_mul_f32_e32 v231, 0xbfb8aa3b, v54
	v_exp_f32_e32 v233, v231
	v_rcp_f32_e32 v231, v211
	v_add_f32_e32 v211, 1.0, v229
	v_mul_f32_e32 v229, 0xbfb8aa3b, v58
	v_exp_f32_e32 v229, v229
	v_rcp_f32_e32 v232, v211
	v_add_f32_e32 v211, 1.0, v233
	v_mul_f32_e32 v233, 0xbfb8aa3b, v50
	v_exp_f32_e32 v233, v233
	v_rcp_f32_e32 v234, v211
	v_add_f32_e32 v211, 1.0, v229
	v_mul_f32_e32 v229, 0xbfb8aa3b, v63
	v_exp_f32_e32 v229, v229
	v_rcp_f32_e32 v236, v211
	v_add_f32_e32 v211, 1.0, v233
	v_mul_f32_e32 v233, 0xbfb8aa3b, v55
	v_exp_f32_e32 v235, v233
	v_rcp_f32_e32 v238, v211
	v_add_f32_e32 v211, 1.0, v229
	v_mul_f32_e32 v229, 0xbfb8aa3b, v59
	v_exp_f32_e32 v229, v229
	v_rcp_f32_e32 v233, v211
	v_add_f32_e32 v211, 1.0, v235
	v_mul_f32_e32 v235, 0xbfb8aa3b, v51
	v_exp_f32_e32 v239, v235
	v_rcp_f32_e32 v235, v211
	v_add_f32_e32 v211, 1.0, v229
	v_rcp_f32_e32 v237, v211
	v_pk_mul_f32 v[232:233], v[232:233], v[148:149]
	v_lshlrev_b32_e32 v148, 16, v150
	v_and_b32_e32 v149, 0xffff0000, v150
	v_pk_mul_f32 v[218:219], v[218:219], v[148:149]
	v_lshlrev_b32_e32 v148, 16, v151
	v_and_b32_e32 v149, 0xffff0000, v151
	v_pk_mul_f32 v[236:237], v[236:237], v[148:149]
	s_waitcnt vmcnt(0)
	v_pk_add_f32 v[148:149], v[200:201], v[206:207]
	v_pk_add_f32 v[150:151], v[202:203], v[204:205]
	v_mov_b32_e32 v200, v148
	v_mov_b32_e32 v201, v208
	v_mov_b32_e32 v208, v149
	v_pk_add_f32 v[148:149], v[200:201], v[208:209]
	v_mov_b32_e32 v200, v151
	v_mov_b32_e32 v201, v213
	v_pk_add_f32 v[148:149], v[200:201], v[148:149]
	v_mov_b32_e32 v151, v212
	v_pk_add_f32 v[148:149], v[150:151], v[148:149]
	v_add_u32_e32 v174, 0x80, v210
	v_pk_fma_f32 v[200:201], v[148:149], s[10:11], v[156:157] op_sel_hi:[1,0,0]
	v_add_f32_e32 v211, 1.0, v239
	v_mul_f32_e32 v148, 0x4b800000, v201
	v_cmp_gt_f32_e32 vcc, s70, v201
	v_pk_mul_f32 v[214:215], v[214:215], v[240:241]
	v_rcp_f32_e32 v239, v211
	v_cndmask_b32_e32 v148, v201, v148, vcc
	v_rsq_f32_e32 v150, v148
	v_mad_i64_i32 v[148:149], s[0:1], v174, s40, v[152:153]
	v_lshl_add_u64 v[202:203], v[148:149], 0, v[154:155]
	v_mul_f32_e32 v148, 0x45800000, v150
	v_cndmask_b32_e32 v174, v150, v148, vcc
	v_pk_mul_f32 v[148:149], v[214:215], v[174:175] op_sel_hi:[1,0]
	v_pk_mul_f32 v[150:151], v[232:233], v[174:175] op_sel_hi:[1,0]
	v_pk_mul_f32 v[216:217], v[52:53], v[216:217]
	v_pk_mul_f32 v[234:235], v[54:55], v[234:235]
	v_pk_mul_f32 v[148:149], v[132:133], v[148:149]
	v_pk_mul_f32 v[150:151], v[134:135], v[150:151]
	v_pk_mul_f32 v[148:149], v[216:217], v[148:149]
	v_pk_mul_f32 v[150:151], v[234:235], v[150:151]
	v_cvt_pk_bf16_f32 v148, v148, v149
	v_cvt_pk_bf16_f32 v149, v150, v151
	v_pk_mul_f32 v[150:151], v[218:219], v[174:175] op_sel_hi:[1,0]
	v_pk_mul_f32 v[204:205], v[236:237], v[174:175] op_sel_hi:[1,0]
	v_pk_mul_f32 v[230:231], v[48:49], v[230:231]
	v_pk_mul_f32 v[238:239], v[50:51], v[238:239]
	v_pk_mul_f32 v[150:151], v[128:129], v[150:151]
	v_pk_mul_f32 v[204:205], v[130:131], v[204:205]
	v_mul_f32_e32 v174, 0x4b800000, v200
	v_cmp_gt_f32_e32 vcc, s70, v200
	v_pk_mul_f32 v[150:151], v[230:231], v[150:151]
	v_pk_mul_f32 v[204:205], v[238:239], v[204:205]
	v_cndmask_b32_e32 v174, v200, v174, vcc
	v_add_co_u32_e64 v200, s[0:1], s75, v202
	v_cvt_pk_bf16_f32 v150, v150, v151
	v_cvt_pk_bf16_f32 v151, v204, v205
	v_addc_co_u32_e64 v201, s[0:1], 0, v203, s[0:1]
	global_store_dwordx4 v[200:201], v[148:151], off
	v_rsq_f32_e32 v174, v174
	v_mul_f32_e32 v201, 0xbfb8aa3b, v33
	v_mul_f32_e32 v149, 0xbfb8aa3b, v44
	v_exp_f32_e32 v149, v149
	v_mul_f32_e32 v150, 0xbfb8aa3b, v36
	v_exp_f32_e32 v151, v150
	v_mul_f32_e32 v148, 0x45800000, v174
	v_add_f32_e32 v149, 1.0, v149
	v_rcp_f32_e32 v150, v149
	v_add_f32_e32 v149, 1.0, v151
	v_mul_f32_e32 v151, 0xbfb8aa3b, v40
	v_cndmask_b32_e32 v148, v174, v148, vcc
	v_exp_f32_e32 v151, v151
	v_mul_f32_e32 v174, 0xbfb8aa3b, v32
	v_exp_f32_e32 v174, v174
	v_rcp_f32_e32 v200, v149
	v_add_f32_e32 v149, 1.0, v151
	v_mul_f32_e32 v151, 0xbfb8aa3b, v45
	v_rcp_f32_e32 v202, v149
	v_add_f32_e32 v149, 1.0, v174
	v_exp_f32_e32 v151, v151
	v_mul_f32_e32 v174, 0xbfb8aa3b, v37
	v_exp_f32_e32 v174, v174
	v_rcp_f32_e32 v204, v149
	v_add_f32_e32 v149, 1.0, v151
	v_rcp_f32_e32 v151, v149
	v_add_f32_e32 v149, 1.0, v174
	v_mul_f32_e32 v174, 0xbfb8aa3b, v41
	v_exp_f32_e32 v174, v174
	v_exp_f32_e32 v205, v201
	v_rcp_f32_e32 v201, v149
	v_pk_add_f32 v[188:189], v[190:191], v[188:189]
	v_add_f32_e32 v149, 1.0, v174
	v_mul_f32_e32 v174, 0xbfb8aa3b, v46
	v_rcp_f32_e32 v203, v149
	v_add_f32_e32 v149, 1.0, v205
	v_exp_f32_e32 v174, v174
	v_mul_f32_e32 v205, 0xbfb8aa3b, v38
	v_exp_f32_e32 v207, v205
	v_rcp_f32_e32 v205, v149
	v_add_f32_e32 v149, 1.0, v174
	v_mul_f32_e32 v174, 0xbfb8aa3b, v42
	v_rcp_f32_e32 v206, v149
	v_add_f32_e32 v149, 1.0, v207
	v_exp_f32_e32 v174, v174
	v_mul_f32_e32 v207, 0xbfb8aa3b, v34
	v_exp_f32_e32 v207, v207
	v_rcp_f32_e32 v208, v149
	v_add_f32_e32 v149, 1.0, v174
	v_mul_f32_e32 v174, 0xbfb8aa3b, v47
	v_rcp_f32_e32 v212, v149
	v_add_f32_e32 v149, 1.0, v207
	v_exp_f32_e32 v174, v174
	v_mul_f32_e32 v207, 0xbfb8aa3b, v39
	v_exp_f32_e32 v209, v207
	v_rcp_f32_e32 v214, v149
	v_add_f32_e32 v149, 1.0, v174
	v_mul_f32_e32 v174, 0xbfb8aa3b, v43
	v_rcp_f32_e32 v207, v149
	v_add_f32_e32 v149, 1.0, v209
	v_exp_f32_e32 v174, v174
	v_mul_f32_e32 v209, 0xbfb8aa3b, v35
	v_exp_f32_e32 v211, v209
	v_rcp_f32_e32 v209, v149
	v_add_f32_e32 v149, 1.0, v174
	v_rcp_f32_e32 v213, v149
	v_add_f32_e32 v149, 1.0, v211
	v_add_u32_e32 v174, 0x90, v210
	v_lshlrev_b32_e32 v210, 16, v144
	v_and_b32_e32 v211, 0xffff0000, v144
	v_pk_mul_f32 v[150:151], v[150:151], v[210:211]
	v_pk_mul_f32 v[200:201], v[36:37], v[200:201]
	v_pk_mul_f32 v[150:151], v[150:151], v[148:149] op_sel_hi:[1,0]
	v_rcp_f32_e32 v215, v149
	v_pk_mul_f32 v[150:151], v[132:133], v[150:151]
	v_pk_add_f32 v[162:163], v[162:163], v[186:187]
	v_pk_mul_f32 v[150:151], v[200:201], v[150:151]
	v_pk_mul_f32 v[200:201], v[38:39], v[208:209]
	v_cvt_pk_bf16_f32 v144, v150, v151
	v_lshlrev_b32_e32 v150, 16, v145
	v_and_b32_e32 v151, 0xffff0000, v145
	v_pk_mul_f32 v[150:151], v[206:207], v[150:151]
	v_mov_b32_e32 v186, v188
	v_pk_mul_f32 v[150:151], v[150:151], v[148:149] op_sel_hi:[1,0]
	s_nop 0
	v_pk_mul_f32 v[150:151], v[134:135], v[150:151]
	s_nop 0
	v_pk_mul_f32 v[150:151], v[200:201], v[150:151]
	v_pk_mul_f32 v[200:201], v[32:33], v[204:205]
	v_cvt_pk_bf16_f32 v145, v150, v151
	v_lshlrev_b32_e32 v150, 16, v146
	v_and_b32_e32 v151, 0xffff0000, v146
	v_pk_mul_f32 v[150:151], v[202:203], v[150:151]
	s_nop 0
	v_pk_mul_f32 v[150:151], v[150:151], v[148:149] op_sel_hi:[1,0]
	s_nop 0
	v_pk_mul_f32 v[150:151], v[128:129], v[150:151]
	s_nop 0
	v_pk_mul_f32 v[150:151], v[200:201], v[150:151]
	v_lshlrev_b32_e32 v200, 16, v140
	v_cvt_pk_bf16_f32 v146, v150, v151
	v_lshlrev_b32_e32 v150, 16, v147
	v_and_b32_e32 v151, 0xffff0000, v147
	v_pk_mul_f32 v[150:151], v[212:213], v[150:151]
	v_and_b32_e32 v201, 0xffff0000, v140
	v_pk_mul_f32 v[148:149], v[150:151], v[148:149] op_sel_hi:[1,0]
	v_pk_mul_f32 v[150:151], v[34:35], v[214:215]
	v_pk_mul_f32 v[148:149], v[130:131], v[148:149]
	v_lshlrev_b32_e32 v140, 16, v141
	v_pk_mul_f32 v[148:149], v[150:151], v[148:149]
	v_mul_f32_e32 v150, 0xbfb8aa3b, v24
	v_cvt_pk_bf16_f32 v147, v148, v149
	v_mad_i64_i32 v[148:149], s[0:1], v174, s40, v[152:153]
	v_lshl_add_u64 v[148:149], v[148:149], 0, v[154:155]
	v_add_co_u32_e32 v148, vcc, s75, v148
	v_mul_f32_e32 v174, 0xbfb8aa3b, v30
	s_nop 0
	v_addc_co_u32_e32 v149, vcc, 0, v149, vcc
	global_store_dwordx4 v[148:149], v[144:147], off
	v_exp_f32_e32 v174, v174
	v_exp_f32_e32 v151, v150
	v_mul_f32_e32 v146, 0xbfb8aa3b, v28
	v_exp_f32_e32 v148, v146
	v_mul_f32_e32 v146, 0xbfb8aa3b, v20
	v_pk_add_f32 v[144:145], v[192:193], v[198:199]
	v_exp_f32_e32 v149, v146
	v_mul_f32_e32 v192, 0xbfb8aa3b, v22
	v_mul_f32_e32 v150, 0xbfb8aa3b, v16
	v_exp_f32_e32 v193, v192
	v_exp_f32_e32 v153, v150
	v_add_f32_e32 v149, 1.0, v149
	v_add_f32_e32 v174, 1.0, v174
	v_rcp_f32_e32 v150, v149
	v_add_f32_e32 v149, 1.0, v151
	v_rcp_f32_e32 v192, v174
	v_add_f32_e32 v174, 1.0, v193
	v_mul_f32_e32 v193, 0xbfb8aa3b, v26
	v_rcp_f32_e32 v152, v149
	v_add_f32_e32 v149, 1.0, v153
	v_mul_f32_e32 v151, 0xbfb8aa3b, v29
	v_mul_f32_e32 v153, 0xbfb8aa3b, v21
	v_exp_f32_e32 v193, v193
	v_pk_add_f32 v[146:147], v[194:195], v[196:197]
	v_exp_f32_e32 v151, v151
	v_exp_f32_e32 v153, v153
	v_mul_f32_e32 v194, 0xbfb8aa3b, v18
	v_exp_f32_e32 v195, v194
	v_rcp_f32_e32 v194, v174
	v_add_f32_e32 v174, 1.0, v193
	v_mul_f32_e32 v193, 0xbfb8aa3b, v31
	v_rcp_f32_e32 v154, v149
	v_add_f32_e32 v149, 1.0, v151
	v_add_f32_e32 v151, 1.0, v153
	v_mul_f32_e32 v153, 0xbfb8aa3b, v25
	v_exp_f32_e32 v193, v193
	v_exp_f32_e32 v153, v153
	v_rcp_f32_e32 v196, v174
	v_add_f32_e32 v174, 1.0, v195
	v_mul_f32_e32 v195, 0xbfb8aa3b, v23
	v_exp_f32_e32 v195, v195
	v_rcp_f32_e32 v198, v174
	v_add_f32_e32 v174, 1.0, v193
	v_add_f32_e32 v153, 1.0, v153
	v_rcp_f32_e32 v193, v174
	v_mov_b32_e32 v187, v144
	v_mov_b32_e32 v144, v189
	v_rcp_f32_e32 v153, v153
	v_add_f32_e32 v174, 1.0, v195
	v_mul_f32_e32 v195, 0xbfb8aa3b, v27
	v_pk_add_f32 v[144:145], v[186:187], v[144:145]
	v_mov_b32_e32 v186, v163
	v_mov_b32_e32 v187, v147
	v_exp_f32_e32 v197, v195
	v_pk_add_f32 v[144:145], v[186:187], v[144:145]
	v_mov_b32_e32 v163, v146
	v_and_b32_e32 v141, 0xffff0000, v141
	v_pk_add_f32 v[144:145], v[162:163], v[144:145]
	v_pk_mul_f32 v[192:193], v[192:193], v[140:141]
	v_lshlrev_b32_e32 v140, 16, v142
	v_and_b32_e32 v141, 0xffff0000, v142
	v_pk_fma_f32 v[144:145], v[144:145], s[10:11], v[156:157] op_sel_hi:[1,0,0]
	v_mul_f32_e32 v195, 0xbfb8aa3b, v19
	v_pk_mul_f32 v[152:153], v[152:153], v[140:141]
	v_mul_f32_e32 v141, 0x4b800000, v145
	v_cmp_gt_f32_e32 vcc, s70, v145
	v_exp_f32_e32 v199, v195
	v_rcp_f32_e32 v195, v174
	v_add_f32_e32 v174, 1.0, v197
	v_cndmask_b32_e32 v141, v145, v141, vcc
	v_add_f32_e32 v148, 1.0, v148
	v_mul_f32_e32 v155, 0xbfb8aa3b, v17
	v_rcp_f32_e32 v197, v174
	v_rsq_f32_e32 v142, v141
	v_rcp_f32_e32 v148, v148
	v_rcp_f32_e32 v149, v149
	v_exp_f32_e32 v155, v155
	v_rcp_f32_e32 v151, v151
	v_lshlrev_b32_e32 v140, 16, v143
	v_and_b32_e32 v141, 0xffff0000, v143
	v_pk_mul_f32 v[146:147], v[196:197], v[140:141]
	v_mul_f32_e32 v140, 0x45800000, v142
	v_add_f32_e32 v155, 1.0, v155
	v_pk_mul_f32 v[148:149], v[148:149], v[200:201]
	v_cndmask_b32_e32 v162, v142, v140, vcc
	v_rcp_f32_e32 v155, v155
	v_pk_mul_f32 v[140:141], v[148:149], v[162:163] op_sel_hi:[1,0]
	v_pk_mul_f32 v[142:143], v[192:193], v[162:163] op_sel_hi:[1,0]
	v_add_f32_e32 v174, 1.0, v199
	v_pk_mul_f32 v[150:151], v[20:21], v[150:151]
	v_pk_mul_f32 v[194:195], v[22:23], v[194:195]
	v_pk_mul_f32 v[140:141], v[132:133], v[140:141]
	v_pk_mul_f32 v[142:143], v[134:135], v[142:143]
	v_rcp_f32_e32 v199, v174
	v_pk_mul_f32 v[140:141], v[150:151], v[140:141]
	v_pk_mul_f32 v[142:143], v[194:195], v[142:143]
	v_cvt_pk_bf16_f32 v140, v140, v141
	v_cvt_pk_bf16_f32 v141, v142, v143
	v_pk_mul_f32 v[142:143], v[152:153], v[162:163] op_sel_hi:[1,0]
	v_pk_mul_f32 v[154:155], v[16:17], v[154:155]
	v_pk_mul_f32 v[142:143], v[128:129], v[142:143]
	v_pk_mul_f32 v[146:147], v[146:147], v[162:163] op_sel_hi:[1,0]
	v_pk_mul_f32 v[142:143], v[154:155], v[142:143]
	v_pk_mul_f32 v[156:157], v[18:19], v[198:199]
	v_cvt_pk_bf16_f32 v142, v142, v143
	v_pk_mul_f32 v[146:147], v[130:131], v[146:147]
	v_mul_f32_e32 v143, 0x4b800000, v144
	v_cmp_gt_f32_e32 vcc, s70, v144
	v_mul_f32_e32 v152, 0xbfb8aa3b, v2
	v_exp_f32_e32 v153, v152
	v_cndmask_b32_e32 v143, v144, v143, vcc
	v_pk_mul_f32 v[144:145], v[156:157], v[146:147]
	v_rsq_f32_e32 v148, v143
	v_cvt_pk_bf16_f32 v143, v144, v145
	global_store_dwordx4 v[160:161], v[140:143], off
	v_mul_f32_e32 v144, 0xbfb8aa3b, v0
	v_exp_f32_e32 v145, v144
	v_mul_f32_e32 v141, 0xbfb8aa3b, v12
	v_exp_f32_e32 v141, v141
	v_mul_f32_e32 v142, 0xbfb8aa3b, v4
	v_exp_f32_e32 v143, v142
	v_mul_f32_e32 v140, 0x45800000, v148
	v_add_f32_e32 v141, 1.0, v141
	v_rcp_f32_e32 v142, v141
	v_add_f32_e32 v141, 1.0, v143
	v_mul_f32_e32 v143, 0xbfb8aa3b, v8
	v_exp_f32_e32 v143, v143
	v_rcp_f32_e32 v144, v141
	v_cndmask_b32_e32 v140, v148, v140, vcc
	v_lshlrev_b32_e32 v160, 16, v136
	v_add_f32_e32 v141, 1.0, v143
	v_mul_f32_e32 v143, 0xbfb8aa3b, v13
	v_rcp_f32_e32 v146, v141
	v_add_f32_e32 v141, 1.0, v145
	v_exp_f32_e32 v143, v143
	v_mul_f32_e32 v145, 0xbfb8aa3b, v5
	v_exp_f32_e32 v145, v145
	v_rcp_f32_e32 v148, v141
	v_add_f32_e32 v141, 1.0, v143
	v_rcp_f32_e32 v143, v141
	v_add_f32_e32 v141, 1.0, v145
	v_mul_f32_e32 v145, 0xbfb8aa3b, v9
	v_exp_f32_e32 v147, v145
	v_mul_f32_e32 v145, 0xbfb8aa3b, v1
	v_exp_f32_e32 v149, v145
	v_rcp_f32_e32 v145, v141
	v_add_f32_e32 v141, 1.0, v147
	v_rcp_f32_e32 v147, v141
	v_add_f32_e32 v141, 1.0, v149
	v_mul_f32_e32 v149, 0xbfb8aa3b, v14
	v_exp_f32_e32 v150, v149
	v_mul_f32_e32 v149, 0xbfb8aa3b, v6
	v_exp_f32_e32 v151, v149
	v_rcp_f32_e32 v149, v141
	v_add_f32_e32 v141, 1.0, v150
	v_rcp_f32_e32 v150, v141
	v_add_f32_e32 v141, 1.0, v151
	v_mul_f32_e32 v151, 0xbfb8aa3b, v10
	v_exp_f32_e32 v151, v151
	v_rcp_f32_e32 v152, v141
	v_and_b32_e32 v161, 0xffff0000, v136
	v_lshlrev_b32_e32 v136, 16, v137
	v_add_f32_e32 v141, 1.0, v151
	v_mul_f32_e32 v151, 0xbfb8aa3b, v15
	v_rcp_f32_e32 v154, v141
	v_add_f32_e32 v141, 1.0, v153
	v_exp_f32_e32 v151, v151
	v_mul_f32_e32 v153, 0xbfb8aa3b, v7
	v_exp_f32_e32 v153, v153
	v_rcp_f32_e32 v156, v141
	v_add_f32_e32 v141, 1.0, v151
	v_rcp_f32_e32 v151, v141
	v_add_f32_e32 v141, 1.0, v153
	v_mul_f32_e32 v153, 0xbfb8aa3b, v11
	v_exp_f32_e32 v155, v153
	v_mul_f32_e32 v153, 0xbfb8aa3b, v3
	v_exp_f32_e32 v157, v153
	v_rcp_f32_e32 v153, v141
	v_add_f32_e32 v141, 1.0, v155
	v_and_b32_e32 v137, 0xffff0000, v137
	v_rcp_f32_e32 v155, v141
	v_add_f32_e32 v141, 1.0, v157
	v_pk_mul_f32 v[142:143], v[142:143], v[160:161]
	v_pk_mul_f32 v[136:137], v[150:151], v[136:137]
	v_pk_mul_f32 v[142:143], v[142:143], v[140:141] op_sel_hi:[1,0]
	v_pk_mul_f32 v[136:137], v[136:137], v[140:141] op_sel_hi:[1,0]
	v_pk_mul_f32 v[132:133], v[132:133], v[142:143]
	v_pk_mul_f32 v[142:143], v[4:5], v[144:145]
	v_pk_mul_f32 v[134:135], v[134:135], v[136:137]
	v_pk_mul_f32 v[136:137], v[6:7], v[152:153]
	v_pk_mul_f32 v[132:133], v[142:143], v[132:133]
	v_pk_mul_f32 v[134:135], v[136:137], v[134:135]
	v_cvt_pk_bf16_f32 v132, v132, v133
	v_cvt_pk_bf16_f32 v133, v134, v135
	v_lshlrev_b32_e32 v134, 16, v138
	v_and_b32_e32 v135, 0xffff0000, v138
	v_pk_mul_f32 v[134:135], v[146:147], v[134:135]
	v_rcp_f32_e32 v157, v141
	v_pk_mul_f32 v[134:135], v[134:135], v[140:141] op_sel_hi:[1,0]
	s_nop 0
	v_pk_mul_f32 v[128:129], v[128:129], v[134:135]
	v_pk_mul_f32 v[134:135], v[0:1], v[148:149]
	s_nop 0
	v_pk_mul_f32 v[128:129], v[134:135], v[128:129]
	s_nop 0
	v_cvt_pk_bf16_f32 v134, v128, v129
	v_lshlrev_b32_e32 v128, 16, v139
	v_and_b32_e32 v129, 0xffff0000, v139
	v_pk_mul_f32 v[128:129], v[154:155], v[128:129]
	s_nop 0
	v_pk_mul_f32 v[128:129], v[128:129], v[140:141] op_sel_hi:[1,0]
	s_nop 0
	v_pk_mul_f32 v[128:129], v[130:131], v[128:129]
	v_pk_mul_f32 v[130:131], v[2:3], v[156:157]
	s_nop 0
	v_pk_mul_f32 v[128:129], v[130:131], v[128:129]
	s_nop 0
	v_cvt_pk_bf16_f32 v135, v128, v129
	global_store_dwordx4 v[158:159], v[132:135], off
